# v61 + EpiRes epilogues (wout, MLP2): the second half's 8 residual loads are issued at the start of the epilogue into dead K-loop fragment VGPRs, all vmcnt waits replaced by exact counted waits
# baseline (speedup 1.0000x reference)
; __device__ __forceinline__ float bflo_(unsigned w) { return __uint_as_float(w << 16); }
; __device__ __forceinline__ float bfhi_(unsigned w) { return __uint_as_float(w & 0xffff0000u); }
; __device__ __forceinline__ unsigned cvt_pk_bf16(float lo, float hi) { unsigned r; asm volatile("v_cvt_pk_bf16_f32 %0, %1, %2" : "=v"(r) : "v"(lo), "v"(hi)); return r; }
; #define PG8_OPQ(p) asm volatile("" : "+v"(p))
;     __device__ __forceinline__ void operator()(const f32x4 (&acc)[2][2][4][2], const Unit& u, int wr, int wc, int fr, int fq) const {
;     ...
;         for (int ai = 0; ai < 2; ++ai) {
;             PG8_OPQ(p);
;             u32x4 h[4][2];
; #pragma unroll
;             for (int m = 0; m < 4; ++m)
; #pragma unroll
;                 for (int bj = 0; bj < 2; ++bj) h[m][bj] = *(const u32x4*)(p + m * step + bj * HALF * 2);
; #pragma unroll
;             for (int m = 0; m < 4; ++m)
; #pragma unroll
;                 for (int bj = 0; bj < 2; ++bj) { const f32x4 v0 = acc[ai][bj][m][0], v1 = acc[ai][bj][m][1]; const u32x4 hh = h[m][bj];
;                     u32x4 w;
;                     w.x = cvt_pk_bf16(bflo_(hh.x) * alpha + v0[0], bfhi_(hh.x) * alpha + v0[1]); w.y = cvt_pk_bf16(bflo_(hh.y) * alpha + v0[2], bfhi_(hh.y) * alpha + v0[3]);
;                     w.z = cvt_pk_bf16(bflo_(hh.z) * alpha + v1[0], bfhi_(hh.z) * alpha + v1[1]); w.w = cvt_pk_bf16(bflo_(hh.w) * alpha + v1[2], bfhi_(hh.w) * alpha + v1[3]);
;                     *(u32x4*)(p + m * step + bj * HALF * 2) = w; }
;             p += 8 * step;
.LBB0_421:
	s_lshl_b32 s36, s8, 8
	v_lshl_add_u64 v[154:155], s[36:37], 1, v[148:149]
	global_load_dwordx4 v[162:165], v[154:155], off
	global_load_dwordx4 v[166:169], v[154:155], off offset:256
	v_add_co_u32_e32 v182, vcc, 0x8000, v154
	s_cmp_eq_u32 s8, 3
	s_nop 0
	v_addc_co_u32_e32 v183, vcc, 0, v155, vcc
	global_load_dwordx4 v[170:173], v[182:183], off
	global_load_dwordx4 v[174:177], v[182:183], off offset:256
	v_add_co_u32_e32 v158, vcc, 0x10000, v154
	s_mov_b64 s[8:9], -1
	s_nop 0
	v_addc_co_u32_e32 v159, vcc, 0, v155, vcc
	global_load_dwordx4 v[178:181], v[158:159], off
	global_load_dwordx4 v[138:141], v[158:159], off offset:256
	v_add_co_u32_e32 v156, vcc, 0x18000, v154
	v_addc_co_u32_e32 v157, vcc, 0, v155, vcc
	global_load_dwordx4 v[134:137], v[156:157], off
	global_load_dwordx4 v[130:133], v[156:157], off offset:256
	v_lshl_add_u64 v[254:255], v[154:155], 0, s[24:25]
	global_load_dwordx4 v[196:199], v[254:255], off
	global_load_dwordx4 v[200:203], v[254:255], off offset:256
	v_add_co_u32_e32 v224, vcc, s87, v254
	s_nop 1
	v_addc_co_u32_e32 v225, vcc, 0, v255, vcc
	global_load_dwordx4 v[204:207], v[224:225], off
	global_load_dwordx4 v[208:211], v[224:225], off offset:256
	v_add_co_u32_e32 v224, vcc, s91, v254
	s_nop 1
	v_addc_co_u32_e32 v225, vcc, 0, v255, vcc
	global_load_dwordx4 v[212:215], v[224:225], off
	global_load_dwordx4 v[216:219], v[224:225], off offset:256
	v_add_co_u32_e32 v224, vcc, s86, v254
	s_nop 1
	v_addc_co_u32_e32 v225, vcc, 0, v255, vcc
	global_load_dwordx4 v[238:241], v[224:225], off
	global_load_dwordx4 v[244:247], v[224:225], off offset:256
	s_waitcnt vmcnt(15) lgkmcnt(0)
	v_lshlrev_b32_e32 v184, 16, v162
	v_and_b32_e32 v162, 0xffff0000, v162
	v_lshlrev_b32_e32 v185, 16, v163
	v_and_b32_e32 v163, 0xffff0000, v163
	v_lshlrev_b32_e32 v186, 16, v164
	v_and_b32_e32 v164, 0xffff0000, v164
	v_lshlrev_b32_e32 v187, 16, v165
	v_and_b32_e32 v165, 0xffff0000, v165
	v_fmac_f32_e32 v122, 0x3fb504f3, v184
	v_fmac_f32_e32 v123, 0x3fb504f3, v162
	v_fmac_f32_e32 v124, 0x3fb504f3, v185
	v_fmac_f32_e32 v125, 0x3fb504f3, v163
	v_fmac_f32_e32 v126, 0x3fb504f3, v186
	v_fmac_f32_e32 v127, 0x3fb504f3, v164
	v_fmac_f32_e32 v128, 0x3fb504f3, v187
	s_waitcnt vmcnt(14)
	v_lshlrev_b32_e32 v188, 16, v166
	v_and_b32_e32 v166, 0xffff0000, v166
	v_lshlrev_b32_e32 v190, 16, v167
	v_and_b32_e32 v167, 0xffff0000, v167
	v_fmac_f32_e32 v129, 0x3fb504f3, v165
	v_cvt_pk_bf16_f32 v122, v122, v123
	v_cvt_pk_bf16_f32 v123, v124, v125
	v_cvt_pk_bf16_f32 v124, v126, v127
	v_cvt_pk_bf16_f32 v125, v128, v129
	s_waitcnt vmcnt(13)
	v_lshlrev_b32_e32 v126, 16, v170
	v_and_b32_e32 v127, 0xffff0000, v170
	v_lshlrev_b32_e32 v128, 16, v171
	v_lshlrev_b32_e32 v162, 16, v172
	v_lshlrev_b32_e32 v192, 16, v168
	v_and_b32_e32 v168, 0xffff0000, v168
	v_lshlrev_b32_e32 v193, 16, v169
	v_and_b32_e32 v169, 0xffff0000, v169
	v_fmac_f32_e32 v118, 0x3fb504f3, v188
	v_fmac_f32_e32 v119, 0x3fb504f3, v166
	v_fmac_f32_e32 v120, 0x3fb504f3, v190
	v_fmac_f32_e32 v121, 0x3fb504f3, v167
	v_and_b32_e32 v129, 0xffff0000, v171
	v_and_b32_e32 v163, 0xffff0000, v172
	v_fmac_f32_e32 v110, 0x3fb504f3, v126
	v_fmac_f32_e32 v111, 0x3fb504f3, v127
	v_fmac_f32_e32 v112, 0x3fb504f3, v128
	v_fmac_f32_e32 v106, 0x3fb504f3, v162
	v_fmac_f32_e32 v114, 0x3fb504f3, v192
	v_fmac_f32_e32 v115, 0x3fb504f3, v168
	v_fmac_f32_e32 v116, 0x3fb504f3, v193
	v_fmac_f32_e32 v117, 0x3fb504f3, v169
	global_store_dwordx4 v[154:155], v[122:125], off
	v_cvt_pk_bf16_f32 v118, v118, v119
	v_cvt_pk_bf16_f32 v119, v120, v121
	v_cvt_pk_bf16_f32 v120, v114, v115
	v_cvt_pk_bf16_f32 v121, v116, v117
	v_fmac_f32_e32 v113, 0x3fb504f3, v129
	v_fmac_f32_e32 v107, 0x3fb504f3, v163
	global_store_dwordx4 v[154:155], v[118:121], off offset:256
	v_cvt_pk_bf16_f32 v110, v110, v111
	v_cvt_pk_bf16_f32 v111, v112, v113
	v_cvt_pk_bf16_f32 v112, v106, v107
	s_waitcnt vmcnt(14)
	v_lshlrev_b32_e32 v106, 16, v174
	v_fmac_f32_e32 v102, 0x3fb504f3, v106
	v_and_b32_e32 v106, 0xffff0000, v174
	v_lshlrev_b32_e32 v164, 16, v173
	v_and_b32_e32 v165, 0xffff0000, v173
	v_fmac_f32_e32 v103, 0x3fb504f3, v106
	v_fmac_f32_e32 v108, 0x3fb504f3, v164
	v_fmac_f32_e32 v109, 0x3fb504f3, v165
	v_cvt_pk_bf16_f32 v113, v108, v109
	global_store_dwordx4 v[182:183], v[110:113], off
	v_cvt_pk_bf16_f32 v102, v102, v103
	v_lshlrev_b32_e32 v103, 16, v175
	v_fmac_f32_e32 v104, 0x3fb504f3, v103
	v_and_b32_e32 v103, 0xffff0000, v175
	v_fmac_f32_e32 v105, 0x3fb504f3, v103
	v_cvt_pk_bf16_f32 v103, v104, v105
	v_lshlrev_b32_e32 v104, 16, v176
	v_fmac_f32_e32 v98, 0x3fb504f3, v104
	v_and_b32_e32 v104, 0xffff0000, v176
	v_fmac_f32_e32 v99, 0x3fb504f3, v104
	v_cvt_pk_bf16_f32 v104, v98, v99
	v_lshlrev_b32_e32 v98, 16, v177
	v_fmac_f32_e32 v100, 0x3fb504f3, v98
	v_and_b32_e32 v98, 0xffff0000, v177
	v_fmac_f32_e32 v101, 0x3fb504f3, v98
	s_waitcnt vmcnt(14)
	v_lshlrev_b32_e32 v98, 16, v178
	v_fmac_f32_e32 v94, 0x3fb504f3, v98
	v_and_b32_e32 v98, 0xffff0000, v178
	v_fmac_f32_e32 v95, 0x3fb504f3, v98
	v_cvt_pk_bf16_f32 v105, v100, v101
	global_store_dwordx4 v[182:183], v[102:105], off offset:256
	v_cvt_pk_bf16_f32 v94, v94, v95
	v_lshlrev_b32_e32 v95, 16, v179
	v_fmac_f32_e32 v96, 0x3fb504f3, v95
	v_and_b32_e32 v95, 0xffff0000, v179
	v_fmac_f32_e32 v97, 0x3fb504f3, v95
	v_cvt_pk_bf16_f32 v95, v96, v97
	v_lshlrev_b32_e32 v96, 16, v180
	v_fmac_f32_e32 v90, 0x3fb504f3, v96
	v_and_b32_e32 v96, 0xffff0000, v180
	v_fmac_f32_e32 v91, 0x3fb504f3, v96
	v_cvt_pk_bf16_f32 v96, v90, v91
	v_lshlrev_b32_e32 v90, 16, v181
	v_fmac_f32_e32 v92, 0x3fb504f3, v90
	v_and_b32_e32 v90, 0xffff0000, v181
	v_fmac_f32_e32 v93, 0x3fb504f3, v90
	s_waitcnt vmcnt(14)
; __device__ __forceinline__ float bflo_(unsigned w) { return __uint_as_float(w << 16); }
; __device__ __forceinline__ float bfhi_(unsigned w) { return __uint_as_float(w & 0xffff0000u); }
; __device__ __forceinline__ unsigned cvt_pk_bf16(float lo, float hi) { unsigned r; asm volatile("v_cvt_pk_bf16_f32 %0, %1, %2" : "=v"(r) : "v"(lo), "v"(hi)); return r; }
; #define PG8_OPQ(p) asm volatile("" : "+v"(p))
;     __device__ __forceinline__ void operator()(const f32x4 (&acc)[2][2][4][2], const Unit& u, int wr, int wc, int fr, int fq) const {
;     ...
;         for (int ai = 0; ai < 2; ++ai) {
;             PG8_OPQ(p);
;             u32x4 h[4][2];
; #pragma unroll
;             for (int m = 0; m < 4; ++m)
; #pragma unroll
;                 for (int bj = 0; bj < 2; ++bj) h[m][bj] = *(const u32x4*)(p + m * step + bj * HALF * 2);
; #pragma unroll
;             for (int m = 0; m < 4; ++m)
; #pragma unroll
;                 for (int bj = 0; bj < 2; ++bj) { const f32x4 v0 = acc[ai][bj][m][0], v1 = acc[ai][bj][m][1]; const u32x4 hh = h[m][bj];
;                     u32x4 w;
;                     w.x = cvt_pk_bf16(bflo_(hh.x) * alpha + v0[0], bfhi_(hh.x) * alpha + v0[1]); w.y = cvt_pk_bf16(bflo_(hh.y) * alpha + v0[2], bfhi_(hh.y) * alpha + v0[3]);
;                     w.z = cvt_pk_bf16(bflo_(hh.z) * alpha + v1[0], bfhi_(hh.z) * alpha + v1[1]); w.w = cvt_pk_bf16(bflo_(hh.w) * alpha + v1[2], bfhi_(hh.w) * alpha + v1[3]);
;                     *(u32x4*)(p + m * step + bj * HALF * 2) = w; }
;             p += 8 * step;
	v_lshlrev_b32_e32 v90, 16, v138
	v_fmac_f32_e32 v86, 0x3fb504f3, v90
	v_and_b32_e32 v90, 0xffff0000, v138
	v_fmac_f32_e32 v87, 0x3fb504f3, v90
	v_cvt_pk_bf16_f32 v97, v92, v93
	global_store_dwordx4 v[158:159], v[94:97], off
	v_cvt_pk_bf16_f32 v86, v86, v87
	v_lshlrev_b32_e32 v87, 16, v139
	v_fmac_f32_e32 v88, 0x3fb504f3, v87
	v_and_b32_e32 v87, 0xffff0000, v139
	v_fmac_f32_e32 v89, 0x3fb504f3, v87
	v_cvt_pk_bf16_f32 v87, v88, v89
	v_lshlrev_b32_e32 v88, 16, v140
	v_fmac_f32_e32 v82, 0x3fb504f3, v88
	v_and_b32_e32 v88, 0xffff0000, v140
	v_fmac_f32_e32 v83, 0x3fb504f3, v88
	v_cvt_pk_bf16_f32 v88, v82, v83
	v_lshlrev_b32_e32 v82, 16, v141
	v_fmac_f32_e32 v84, 0x3fb504f3, v82
	v_and_b32_e32 v82, 0xffff0000, v141
	v_fmac_f32_e32 v85, 0x3fb504f3, v82
	s_waitcnt vmcnt(14)
	v_lshlrev_b32_e32 v82, 16, v134
	v_fmac_f32_e32 v78, 0x3fb504f3, v82
	v_and_b32_e32 v82, 0xffff0000, v134
	v_fmac_f32_e32 v79, 0x3fb504f3, v82
	v_cvt_pk_bf16_f32 v89, v84, v85
	global_store_dwordx4 v[158:159], v[86:89], off offset:256
	v_cvt_pk_bf16_f32 v78, v78, v79
	v_lshlrev_b32_e32 v79, 16, v135
	v_fmac_f32_e32 v80, 0x3fb504f3, v79
	v_and_b32_e32 v79, 0xffff0000, v135
	v_fmac_f32_e32 v81, 0x3fb504f3, v79
	v_cvt_pk_bf16_f32 v79, v80, v81
	v_lshlrev_b32_e32 v80, 16, v136
	v_fmac_f32_e32 v74, 0x3fb504f3, v80
	v_and_b32_e32 v80, 0xffff0000, v136
	v_fmac_f32_e32 v75, 0x3fb504f3, v80
	v_cvt_pk_bf16_f32 v80, v74, v75
	v_lshlrev_b32_e32 v74, 16, v137
	v_fmac_f32_e32 v76, 0x3fb504f3, v74
	v_and_b32_e32 v74, 0xffff0000, v137
	v_fmac_f32_e32 v77, 0x3fb504f3, v74
	s_waitcnt vmcnt(14)
	v_lshlrev_b32_e32 v74, 16, v130
	v_fmac_f32_e32 v70, 0x3fb504f3, v74
	v_and_b32_e32 v74, 0xffff0000, v130
	v_fmac_f32_e32 v71, 0x3fb504f3, v74
	v_cvt_pk_bf16_f32 v81, v76, v77
	global_store_dwordx4 v[156:157], v[78:81], off
	v_cvt_pk_bf16_f32 v70, v70, v71
	v_lshlrev_b32_e32 v71, 16, v131
	v_fmac_f32_e32 v72, 0x3fb504f3, v71
	v_and_b32_e32 v71, 0xffff0000, v131
	v_fmac_f32_e32 v73, 0x3fb504f3, v71
	v_cvt_pk_bf16_f32 v71, v72, v73
	v_lshlrev_b32_e32 v72, 16, v132
	v_fmac_f32_e32 v66, 0x3fb504f3, v72
	v_and_b32_e32 v72, 0xffff0000, v132
	v_fmac_f32_e32 v67, 0x3fb504f3, v72
	v_cvt_pk_bf16_f32 v72, v66, v67
	v_lshlrev_b32_e32 v66, 16, v133
	v_fmac_f32_e32 v68, 0x3fb504f3, v66
	v_and_b32_e32 v66, 0xffff0000, v133
	v_lshl_add_u64 v[100:101], v[154:155], 0, s[24:25]
	v_fmac_f32_e32 v69, 0x3fb504f3, v66
	v_cvt_pk_bf16_f32 v73, v68, v69
	global_store_dwordx4 v[156:157], v[70:73], off offset:256
	v_add_co_u32_e32 v102, vcc, s87, v100
	s_waitcnt vmcnt(15)
	v_lshlrev_b32_e32 v106, 16, v196
	v_addc_co_u32_e32 v103, vcc, 0, v101, vcc
	v_add_co_u32_e32 v104, vcc, s91, v100
	v_and_b32_e32 v72, 0xffff0000, v196
	s_nop 0
	v_addc_co_u32_e32 v105, vcc, 0, v101, vcc
	v_add_co_u32_e32 v70, vcc, s86, v100
	v_fmac_f32_e32 v62, 0x3fb504f3, v106
	s_nop 0
	v_addc_co_u32_e32 v71, vcc, 0, v101, vcc
	v_fmac_f32_e32 v63, 0x3fb504f3, v72
	v_cvt_pk_bf16_f32 v62, v62, v63
	v_lshlrev_b32_e32 v63, 16, v197
	v_fmac_f32_e32 v64, 0x3fb504f3, v63
	v_and_b32_e32 v63, 0xffff0000, v197
	v_fmac_f32_e32 v65, 0x3fb504f3, v63
	v_cvt_pk_bf16_f32 v63, v64, v65
	v_lshlrev_b32_e32 v64, 16, v198
	v_fmac_f32_e32 v58, 0x3fb504f3, v64
	v_and_b32_e32 v64, 0xffff0000, v198
	v_fmac_f32_e32 v59, 0x3fb504f3, v64
	v_cvt_pk_bf16_f32 v64, v58, v59
	v_lshlrev_b32_e32 v58, 16, v199
	v_fmac_f32_e32 v60, 0x3fb504f3, v58
	v_and_b32_e32 v58, 0xffff0000, v199
	v_fmac_f32_e32 v61, 0x3fb504f3, v58
	s_waitcnt vmcnt(14)
	v_lshlrev_b32_e32 v58, 16, v200
	v_fmac_f32_e32 v54, 0x3fb504f3, v58
	v_and_b32_e32 v58, 0xffff0000, v200
	v_fmac_f32_e32 v55, 0x3fb504f3, v58
	v_cvt_pk_bf16_f32 v65, v60, v61
	global_store_dwordx4 v[100:101], v[62:65], off
	v_cvt_pk_bf16_f32 v54, v54, v55
	v_lshlrev_b32_e32 v55, 16, v201
	v_fmac_f32_e32 v56, 0x3fb504f3, v55
	v_and_b32_e32 v55, 0xffff0000, v201
	v_fmac_f32_e32 v57, 0x3fb504f3, v55
	v_cvt_pk_bf16_f32 v55, v56, v57
	v_lshlrev_b32_e32 v56, 16, v202
	v_fmac_f32_e32 v50, 0x3fb504f3, v56
	v_and_b32_e32 v56, 0xffff0000, v202
	v_fmac_f32_e32 v51, 0x3fb504f3, v56
	v_cvt_pk_bf16_f32 v56, v50, v51
	v_lshlrev_b32_e32 v50, 16, v203
	v_fmac_f32_e32 v52, 0x3fb504f3, v50
	v_and_b32_e32 v50, 0xffff0000, v203
	v_fmac_f32_e32 v53, 0x3fb504f3, v50
	v_cvt_pk_bf16_f32 v57, v52, v53
	global_store_dwordx4 v[100:101], v[54:57], off offset:256
	s_waitcnt vmcnt(15)
; __device__ __forceinline__ float bflo_(unsigned w) { return __uint_as_float(w << 16); }
; __device__ __forceinline__ float bfhi_(unsigned w) { return __uint_as_float(w & 0xffff0000u); }
; __device__ __forceinline__ unsigned cvt_pk_bf16(float lo, float hi) { unsigned r; asm volatile("v_cvt_pk_bf16_f32 %0, %1, %2" : "=v"(r) : "v"(lo), "v"(hi)); return r; }
; #define PG8_OPQ(p) asm volatile("" : "+v"(p))
;     __device__ __forceinline__ void operator()(const f32x4 (&acc)[2][2][4][2], const Unit& u, int wr, int wc, int fr, int fq) const {
;     ...
;         for (int ai = 0; ai < 2; ++ai) {
;             PG8_OPQ(p);
;             u32x4 h[4][2];
; #pragma unroll
;             for (int m = 0; m < 4; ++m)
; #pragma unroll
;                 for (int bj = 0; bj < 2; ++bj) h[m][bj] = *(const u32x4*)(p + m * step + bj * HALF * 2);
; #pragma unroll
;             for (int m = 0; m < 4; ++m)
; #pragma unroll
;                 for (int bj = 0; bj < 2; ++bj) { const f32x4 v0 = acc[ai][bj][m][0], v1 = acc[ai][bj][m][1]; const u32x4 hh = h[m][bj];
;                     u32x4 w;
;                     w.x = cvt_pk_bf16(bflo_(hh.x) * alpha + v0[0], bfhi_(hh.x) * alpha + v0[1]); w.y = cvt_pk_bf16(bflo_(hh.y) * alpha + v0[2], bfhi_(hh.y) * alpha + v0[3]);
;                     w.z = cvt_pk_bf16(bflo_(hh.z) * alpha + v1[0], bfhi_(hh.z) * alpha + v1[1]); w.w = cvt_pk_bf16(bflo_(hh.w) * alpha + v1[2], bfhi_(hh.w) * alpha + v1[3]);
;                     *(u32x4*)(p + m * step + bj * HALF * 2) = w; }
;             p += 8 * step;
	v_lshlrev_b32_e32 v50, 16, v204
	v_fmac_f32_e32 v46, 0x3fb504f3, v50
	v_and_b32_e32 v50, 0xffff0000, v204
	v_fmac_f32_e32 v47, 0x3fb504f3, v50
	v_cvt_pk_bf16_f32 v46, v46, v47
	v_lshlrev_b32_e32 v47, 16, v205
	v_fmac_f32_e32 v48, 0x3fb504f3, v47
	v_and_b32_e32 v47, 0xffff0000, v205
	v_fmac_f32_e32 v49, 0x3fb504f3, v47
	v_cvt_pk_bf16_f32 v47, v48, v49
	v_lshlrev_b32_e32 v48, 16, v206
	v_fmac_f32_e32 v42, 0x3fb504f3, v48
	v_and_b32_e32 v48, 0xffff0000, v206
	v_fmac_f32_e32 v43, 0x3fb504f3, v48
	v_cvt_pk_bf16_f32 v48, v42, v43
	v_lshlrev_b32_e32 v42, 16, v207
	v_fmac_f32_e32 v44, 0x3fb504f3, v42
	v_and_b32_e32 v42, 0xffff0000, v207
	v_fmac_f32_e32 v45, 0x3fb504f3, v42
	s_waitcnt vmcnt(14)
	v_lshlrev_b32_e32 v42, 16, v208
	v_fmac_f32_e32 v38, 0x3fb504f3, v42
	v_and_b32_e32 v42, 0xffff0000, v208
	v_fmac_f32_e32 v39, 0x3fb504f3, v42
	v_cvt_pk_bf16_f32 v49, v44, v45
	global_store_dwordx4 v[102:103], v[46:49], off
	v_cvt_pk_bf16_f32 v38, v38, v39
	v_lshlrev_b32_e32 v39, 16, v209
	v_fmac_f32_e32 v40, 0x3fb504f3, v39
	v_and_b32_e32 v39, 0xffff0000, v209
	v_fmac_f32_e32 v41, 0x3fb504f3, v39
	v_cvt_pk_bf16_f32 v39, v40, v41
	v_lshlrev_b32_e32 v40, 16, v210
	v_fmac_f32_e32 v34, 0x3fb504f3, v40
	v_and_b32_e32 v40, 0xffff0000, v210
	v_fmac_f32_e32 v35, 0x3fb504f3, v40
	v_cvt_pk_bf16_f32 v40, v34, v35
	v_lshlrev_b32_e32 v34, 16, v211
	v_fmac_f32_e32 v36, 0x3fb504f3, v34
	v_and_b32_e32 v34, 0xffff0000, v211
	v_fmac_f32_e32 v37, 0x3fb504f3, v34
	s_waitcnt vmcnt(14)
	v_lshlrev_b32_e32 v34, 16, v212
	v_fmac_f32_e32 v30, 0x3fb504f3, v34
	v_and_b32_e32 v34, 0xffff0000, v212
	v_fmac_f32_e32 v31, 0x3fb504f3, v34
	v_cvt_pk_bf16_f32 v41, v36, v37
	global_store_dwordx4 v[102:103], v[38:41], off offset:256
	v_cvt_pk_bf16_f32 v30, v30, v31
	v_lshlrev_b32_e32 v31, 16, v213
	v_fmac_f32_e32 v32, 0x3fb504f3, v31
	v_and_b32_e32 v31, 0xffff0000, v213
	v_fmac_f32_e32 v33, 0x3fb504f3, v31
	v_cvt_pk_bf16_f32 v31, v32, v33
	v_lshlrev_b32_e32 v32, 16, v214
	v_fmac_f32_e32 v26, 0x3fb504f3, v32
	v_and_b32_e32 v32, 0xffff0000, v214
	v_fmac_f32_e32 v27, 0x3fb504f3, v32
	v_cvt_pk_bf16_f32 v32, v26, v27
	v_lshlrev_b32_e32 v26, 16, v215
	v_fmac_f32_e32 v28, 0x3fb504f3, v26
	v_and_b32_e32 v26, 0xffff0000, v215
	v_fmac_f32_e32 v29, 0x3fb504f3, v26
	s_waitcnt vmcnt(14)
	v_lshlrev_b32_e32 v26, 16, v216
	v_fmac_f32_e32 v22, 0x3fb504f3, v26
	v_and_b32_e32 v26, 0xffff0000, v216
	v_fmac_f32_e32 v23, 0x3fb504f3, v26
	v_cvt_pk_bf16_f32 v33, v28, v29
	global_store_dwordx4 v[104:105], v[30:33], off
	v_cvt_pk_bf16_f32 v22, v22, v23
	v_lshlrev_b32_e32 v23, 16, v217
	v_fmac_f32_e32 v24, 0x3fb504f3, v23
	v_and_b32_e32 v23, 0xffff0000, v217
	v_fmac_f32_e32 v25, 0x3fb504f3, v23
	v_cvt_pk_bf16_f32 v23, v24, v25
	v_lshlrev_b32_e32 v24, 16, v218
	v_fmac_f32_e32 v18, 0x3fb504f3, v24
	v_and_b32_e32 v24, 0xffff0000, v218
	v_fmac_f32_e32 v19, 0x3fb504f3, v24
	v_cvt_pk_bf16_f32 v24, v18, v19
	v_lshlrev_b32_e32 v18, 16, v219
	v_fmac_f32_e32 v20, 0x3fb504f3, v18
	v_and_b32_e32 v18, 0xffff0000, v219
	v_fmac_f32_e32 v21, 0x3fb504f3, v18
	s_waitcnt vmcnt(14)
	v_lshlrev_b32_e32 v18, 16, v238
	v_fmac_f32_e32 v14, 0x3fb504f3, v18
	v_and_b32_e32 v18, 0xffff0000, v238
	v_fmac_f32_e32 v15, 0x3fb504f3, v18
	v_cvt_pk_bf16_f32 v25, v20, v21
	global_store_dwordx4 v[104:105], v[22:25], off offset:256
	v_cvt_pk_bf16_f32 v14, v14, v15
	v_lshlrev_b32_e32 v15, 16, v239
	v_fmac_f32_e32 v16, 0x3fb504f3, v15
	v_and_b32_e32 v15, 0xffff0000, v239
	v_fmac_f32_e32 v17, 0x3fb504f3, v15
	v_cvt_pk_bf16_f32 v15, v16, v17
	v_lshlrev_b32_e32 v16, 16, v240
	v_fmac_f32_e32 v10, 0x3fb504f3, v16
	v_and_b32_e32 v16, 0xffff0000, v240
	v_fmac_f32_e32 v11, 0x3fb504f3, v16
	v_cvt_pk_bf16_f32 v16, v10, v11
	v_lshlrev_b32_e32 v10, 16, v241
	v_fmac_f32_e32 v12, 0x3fb504f3, v10
	v_and_b32_e32 v10, 0xffff0000, v241
	v_fmac_f32_e32 v13, 0x3fb504f3, v10
	s_waitcnt vmcnt(14)
	v_lshlrev_b32_e32 v10, 16, v244
	v_fmac_f32_e32 v6, 0x3fb504f3, v10
	v_and_b32_e32 v10, 0xffff0000, v244
	v_fmac_f32_e32 v7, 0x3fb504f3, v10
	v_cvt_pk_bf16_f32 v17, v12, v13
	global_store_dwordx4 v[70:71], v[14:17], off
	v_cvt_pk_bf16_f32 v6, v6, v7
	v_lshlrev_b32_e32 v7, 16, v245
	v_fmac_f32_e32 v8, 0x3fb504f3, v7
	v_and_b32_e32 v7, 0xffff0000, v245
	v_fmac_f32_e32 v9, 0x3fb504f3, v7
	v_cvt_pk_bf16_f32 v7, v8, v9
	v_lshlrev_b32_e32 v8, 16, v246
	v_fmac_f32_e32 v2, 0x3fb504f3, v8
	v_and_b32_e32 v8, 0xffff0000, v246
	v_fmac_f32_e32 v3, 0x3fb504f3, v8
	v_cvt_pk_bf16_f32 v8, v2, v3
	v_lshlrev_b32_e32 v2, 16, v247
	v_fmac_f32_e32 v4, 0x3fb504f3, v2
	v_and_b32_e32 v2, 0xffff0000, v247
	v_fmac_f32_e32 v5, 0x3fb504f3, v2
	v_cvt_pk_bf16_f32 v9, v4, v5
	global_store_dwordx4 v[70:71], v[6:9], off offset:256
	s_cbranch_scc1 .LBB0_413
	s_andn2_b64 vcc, exec, s[38:39]
	s_cbranch_vccnz .LBB0_412
	s_barrier
	s_branch .LBB0_412

; __device__ __forceinline__ float bflo_(unsigned w) { return __uint_as_float(w << 16); }
; __device__ __forceinline__ float bfhi_(unsigned w) { return __uint_as_float(w & 0xffff0000u); }
; __device__ __forceinline__ unsigned cvt_pk_bf16(float lo, float hi) { unsigned r; asm volatile("v_cvt_pk_bf16_f32 %0, %1, %2" : "=v"(r) : "v"(lo), "v"(hi)); return r; }
; #define PG8_OPQ(p) asm volatile("" : "+v"(p))
;     __device__ __forceinline__ void operator()(const f32x4 (&acc)[2][2][4][2], const Unit& u, int wr, int wc, int fr, int fq) const {
;     ...
;         for (int ai = 0; ai < 2; ++ai) {
;             PG8_OPQ(p);
;             u32x4 h[4][2];
; #pragma unroll
;             for (int m = 0; m < 4; ++m)
; #pragma unroll
;                 for (int bj = 0; bj < 2; ++bj) h[m][bj] = *(const u32x4*)(p + m * step + bj * HALF * 2);
; #pragma unroll
;             for (int m = 0; m < 4; ++m)
; #pragma unroll
;                 for (int bj = 0; bj < 2; ++bj) { const f32x4 v0 = acc[ai][bj][m][0], v1 = acc[ai][bj][m][1]; const u32x4 hh = h[m][bj];
;                     u32x4 w;
;                     w.x = cvt_pk_bf16(bflo_(hh.x) * alpha + v0[0], bfhi_(hh.x) * alpha + v0[1]); w.y = cvt_pk_bf16(bflo_(hh.y) * alpha + v0[2], bfhi_(hh.y) * alpha + v0[3]);
;                     w.z = cvt_pk_bf16(bflo_(hh.z) * alpha + v1[0], bfhi_(hh.z) * alpha + v1[1]); w.w = cvt_pk_bf16(bflo_(hh.w) * alpha + v1[2], bfhi_(hh.w) * alpha + v1[3]);
;                     *(u32x4*)(p + m * step + bj * HALF * 2) = w; }
;             p += 8 * step;
.LBB0_453:
	s_sub_u32 s36, 3, s8
	s_lshl_b32 s36, s36, 21
	v_lshl_add_u64 v[154:155], s[36:37], 1, v[148:149]
	global_load_dwordx4 v[162:165], v[154:155], off
	global_load_dwordx4 v[166:169], v[154:155], off offset:256
	v_add_co_u32_e32 v182, vcc, 0x8000, v154
	s_cmp_eq_u32 s8, 3
	s_nop 0
	v_addc_co_u32_e32 v183, vcc, 0, v155, vcc
	global_load_dwordx4 v[170:173], v[182:183], off
	global_load_dwordx4 v[174:177], v[182:183], off offset:256
	v_add_co_u32_e32 v158, vcc, 0x10000, v154
	s_mov_b64 s[8:9], -1
	s_nop 0
	v_addc_co_u32_e32 v159, vcc, 0, v155, vcc
	global_load_dwordx4 v[178:181], v[158:159], off
	global_load_dwordx4 v[138:141], v[158:159], off offset:256
	v_add_co_u32_e32 v156, vcc, 0x18000, v154
	v_addc_co_u32_e32 v157, vcc, 0, v155, vcc
	global_load_dwordx4 v[134:137], v[156:157], off
	global_load_dwordx4 v[130:133], v[156:157], off offset:256
	v_lshl_add_u64 v[254:255], v[154:155], 0, s[24:25]
	global_load_dwordx4 v[196:199], v[254:255], off
	global_load_dwordx4 v[200:203], v[254:255], off offset:256
	v_add_co_u32_e32 v224, vcc, s87, v254
	s_nop 1
	v_addc_co_u32_e32 v225, vcc, 0, v255, vcc
	global_load_dwordx4 v[204:207], v[224:225], off
	global_load_dwordx4 v[208:211], v[224:225], off offset:256
	v_add_co_u32_e32 v224, vcc, s91, v254
	s_nop 1
	v_addc_co_u32_e32 v225, vcc, 0, v255, vcc
	global_load_dwordx4 v[212:215], v[224:225], off
	global_load_dwordx4 v[216:219], v[224:225], off offset:256
	v_add_co_u32_e32 v224, vcc, s86, v254
	s_nop 1
	v_addc_co_u32_e32 v225, vcc, 0, v255, vcc
	global_load_dwordx4 v[238:241], v[224:225], off
	global_load_dwordx4 v[244:247], v[224:225], off offset:256
	s_waitcnt vmcnt(15) lgkmcnt(0)
	v_lshlrev_b32_e32 v184, 16, v162
	v_and_b32_e32 v162, 0xffff0000, v162
	v_lshlrev_b32_e32 v185, 16, v163
	v_and_b32_e32 v163, 0xffff0000, v163
	v_lshlrev_b32_e32 v186, 16, v164
	v_and_b32_e32 v164, 0xffff0000, v164
	v_lshlrev_b32_e32 v187, 16, v165
	v_and_b32_e32 v165, 0xffff0000, v165
	v_fmac_f32_e32 v122, 0x3fb504f3, v184
	v_fmac_f32_e32 v123, 0x3fb504f3, v162
	v_fmac_f32_e32 v124, 0x3fb504f3, v185
	v_fmac_f32_e32 v125, 0x3fb504f3, v163
	v_fmac_f32_e32 v126, 0x3fb504f3, v186
	v_fmac_f32_e32 v127, 0x3fb504f3, v164
	v_fmac_f32_e32 v128, 0x3fb504f3, v187
	s_waitcnt vmcnt(14)
	v_lshlrev_b32_e32 v188, 16, v166
	v_and_b32_e32 v166, 0xffff0000, v166
	v_lshlrev_b32_e32 v190, 16, v167
	v_and_b32_e32 v167, 0xffff0000, v167
	v_fmac_f32_e32 v129, 0x3fb504f3, v165
	v_cvt_pk_bf16_f32 v122, v122, v123
	v_cvt_pk_bf16_f32 v123, v124, v125
	v_cvt_pk_bf16_f32 v124, v126, v127
	v_cvt_pk_bf16_f32 v125, v128, v129
	s_waitcnt vmcnt(13)
	v_lshlrev_b32_e32 v126, 16, v170
	v_and_b32_e32 v127, 0xffff0000, v170
	v_lshlrev_b32_e32 v128, 16, v171
	v_lshlrev_b32_e32 v162, 16, v172
	v_lshlrev_b32_e32 v192, 16, v168
	v_and_b32_e32 v168, 0xffff0000, v168
	v_lshlrev_b32_e32 v193, 16, v169
	v_and_b32_e32 v169, 0xffff0000, v169
	v_fmac_f32_e32 v118, 0x3fb504f3, v188
	v_fmac_f32_e32 v119, 0x3fb504f3, v166
	v_fmac_f32_e32 v120, 0x3fb504f3, v190
	v_fmac_f32_e32 v121, 0x3fb504f3, v167
	v_and_b32_e32 v129, 0xffff0000, v171
	v_and_b32_e32 v163, 0xffff0000, v172
	v_fmac_f32_e32 v110, 0x3fb504f3, v126
	v_fmac_f32_e32 v111, 0x3fb504f3, v127
	v_fmac_f32_e32 v112, 0x3fb504f3, v128
	v_fmac_f32_e32 v106, 0x3fb504f3, v162
	v_fmac_f32_e32 v114, 0x3fb504f3, v192
	v_fmac_f32_e32 v115, 0x3fb504f3, v168
	v_fmac_f32_e32 v116, 0x3fb504f3, v193
	v_fmac_f32_e32 v117, 0x3fb504f3, v169
	global_store_dwordx4 v[154:155], v[122:125], off
	v_cvt_pk_bf16_f32 v118, v118, v119
	v_cvt_pk_bf16_f32 v119, v120, v121
	v_cvt_pk_bf16_f32 v120, v114, v115
	v_cvt_pk_bf16_f32 v121, v116, v117
	v_fmac_f32_e32 v113, 0x3fb504f3, v129
	v_fmac_f32_e32 v107, 0x3fb504f3, v163
	global_store_dwordx4 v[154:155], v[118:121], off offset:256
	v_cvt_pk_bf16_f32 v110, v110, v111
	v_cvt_pk_bf16_f32 v111, v112, v113
	v_cvt_pk_bf16_f32 v112, v106, v107
	s_waitcnt vmcnt(14)
	v_lshlrev_b32_e32 v106, 16, v174
	v_fmac_f32_e32 v102, 0x3fb504f3, v106
	v_and_b32_e32 v106, 0xffff0000, v174
	v_lshlrev_b32_e32 v164, 16, v173
	v_and_b32_e32 v165, 0xffff0000, v173
	v_fmac_f32_e32 v103, 0x3fb504f3, v106
	v_fmac_f32_e32 v108, 0x3fb504f3, v164
	v_fmac_f32_e32 v109, 0x3fb504f3, v165
	v_cvt_pk_bf16_f32 v113, v108, v109
	global_store_dwordx4 v[182:183], v[110:113], off
	v_cvt_pk_bf16_f32 v102, v102, v103
	v_lshlrev_b32_e32 v103, 16, v175
	v_fmac_f32_e32 v104, 0x3fb504f3, v103
	v_and_b32_e32 v103, 0xffff0000, v175
	v_fmac_f32_e32 v105, 0x3fb504f3, v103
	v_cvt_pk_bf16_f32 v103, v104, v105
	v_lshlrev_b32_e32 v104, 16, v176
	v_fmac_f32_e32 v98, 0x3fb504f3, v104
	v_and_b32_e32 v104, 0xffff0000, v176
	v_fmac_f32_e32 v99, 0x3fb504f3, v104
	v_cvt_pk_bf16_f32 v104, v98, v99
	v_lshlrev_b32_e32 v98, 16, v177
	v_fmac_f32_e32 v100, 0x3fb504f3, v98
	v_and_b32_e32 v98, 0xffff0000, v177
	v_fmac_f32_e32 v101, 0x3fb504f3, v98
	s_waitcnt vmcnt(14)
	v_lshlrev_b32_e32 v98, 16, v178
	v_fmac_f32_e32 v94, 0x3fb504f3, v98
	v_and_b32_e32 v98, 0xffff0000, v178
	v_fmac_f32_e32 v95, 0x3fb504f3, v98
	v_cvt_pk_bf16_f32 v105, v100, v101
	global_store_dwordx4 v[182:183], v[102:105], off offset:256
	v_cvt_pk_bf16_f32 v94, v94, v95
	v_lshlrev_b32_e32 v95, 16, v179
	v_fmac_f32_e32 v96, 0x3fb504f3, v95
	v_and_b32_e32 v95, 0xffff0000, v179
	v_fmac_f32_e32 v97, 0x3fb504f3, v95
	v_cvt_pk_bf16_f32 v95, v96, v97
	v_lshlrev_b32_e32 v96, 16, v180
	v_fmac_f32_e32 v90, 0x3fb504f3, v96
	v_and_b32_e32 v96, 0xffff0000, v180
	v_fmac_f32_e32 v91, 0x3fb504f3, v96
	v_cvt_pk_bf16_f32 v96, v90, v91
	v_lshlrev_b32_e32 v90, 16, v181
	v_fmac_f32_e32 v92, 0x3fb504f3, v90
	v_and_b32_e32 v90, 0xffff0000, v181
	v_fmac_f32_e32 v93, 0x3fb504f3, v90
	s_waitcnt vmcnt(14)
; __device__ __forceinline__ float bflo_(unsigned w) { return __uint_as_float(w << 16); }
; __device__ __forceinline__ float bfhi_(unsigned w) { return __uint_as_float(w & 0xffff0000u); }
; __device__ __forceinline__ unsigned cvt_pk_bf16(float lo, float hi) { unsigned r; asm volatile("v_cvt_pk_bf16_f32 %0, %1, %2" : "=v"(r) : "v"(lo), "v"(hi)); return r; }
; #define PG8_OPQ(p) asm volatile("" : "+v"(p))
;     __device__ __forceinline__ void operator()(const f32x4 (&acc)[2][2][4][2], const Unit& u, int wr, int wc, int fr, int fq) const {
;     ...
;         for (int ai = 0; ai < 2; ++ai) {
;             PG8_OPQ(p);
;             u32x4 h[4][2];
; #pragma unroll
;             for (int m = 0; m < 4; ++m)
; #pragma unroll
;                 for (int bj = 0; bj < 2; ++bj) h[m][bj] = *(const u32x4*)(p + m * step + bj * HALF * 2);
; #pragma unroll
;             for (int m = 0; m < 4; ++m)
; #pragma unroll
;                 for (int bj = 0; bj < 2; ++bj) { const f32x4 v0 = acc[ai][bj][m][0], v1 = acc[ai][bj][m][1]; const u32x4 hh = h[m][bj];
;                     u32x4 w;
;                     w.x = cvt_pk_bf16(bflo_(hh.x) * alpha + v0[0], bfhi_(hh.x) * alpha + v0[1]); w.y = cvt_pk_bf16(bflo_(hh.y) * alpha + v0[2], bfhi_(hh.y) * alpha + v0[3]);
;                     w.z = cvt_pk_bf16(bflo_(hh.z) * alpha + v1[0], bfhi_(hh.z) * alpha + v1[1]); w.w = cvt_pk_bf16(bflo_(hh.w) * alpha + v1[2], bfhi_(hh.w) * alpha + v1[3]);
;                     *(u32x4*)(p + m * step + bj * HALF * 2) = w; }
;             p += 8 * step;
	v_lshlrev_b32_e32 v90, 16, v138
	v_fmac_f32_e32 v86, 0x3fb504f3, v90
	v_and_b32_e32 v90, 0xffff0000, v138
	v_fmac_f32_e32 v87, 0x3fb504f3, v90
	v_cvt_pk_bf16_f32 v97, v92, v93
	global_store_dwordx4 v[158:159], v[94:97], off
	v_cvt_pk_bf16_f32 v86, v86, v87
	v_lshlrev_b32_e32 v87, 16, v139
	v_fmac_f32_e32 v88, 0x3fb504f3, v87
	v_and_b32_e32 v87, 0xffff0000, v139
	v_fmac_f32_e32 v89, 0x3fb504f3, v87
	v_cvt_pk_bf16_f32 v87, v88, v89
	v_lshlrev_b32_e32 v88, 16, v140
	v_fmac_f32_e32 v82, 0x3fb504f3, v88
	v_and_b32_e32 v88, 0xffff0000, v140
	v_fmac_f32_e32 v83, 0x3fb504f3, v88
	v_cvt_pk_bf16_f32 v88, v82, v83
	v_lshlrev_b32_e32 v82, 16, v141
	v_fmac_f32_e32 v84, 0x3fb504f3, v82
	v_and_b32_e32 v82, 0xffff0000, v141
	v_fmac_f32_e32 v85, 0x3fb504f3, v82
	s_waitcnt vmcnt(14)
	v_lshlrev_b32_e32 v82, 16, v134
	v_fmac_f32_e32 v78, 0x3fb504f3, v82
	v_and_b32_e32 v82, 0xffff0000, v134
	v_fmac_f32_e32 v79, 0x3fb504f3, v82
	v_cvt_pk_bf16_f32 v89, v84, v85
	global_store_dwordx4 v[158:159], v[86:89], off offset:256
	v_cvt_pk_bf16_f32 v78, v78, v79
	v_lshlrev_b32_e32 v79, 16, v135
	v_fmac_f32_e32 v80, 0x3fb504f3, v79
	v_and_b32_e32 v79, 0xffff0000, v135
	v_fmac_f32_e32 v81, 0x3fb504f3, v79
	v_cvt_pk_bf16_f32 v79, v80, v81
	v_lshlrev_b32_e32 v80, 16, v136
	v_fmac_f32_e32 v74, 0x3fb504f3, v80
	v_and_b32_e32 v80, 0xffff0000, v136
	v_fmac_f32_e32 v75, 0x3fb504f3, v80
	v_cvt_pk_bf16_f32 v80, v74, v75
	v_lshlrev_b32_e32 v74, 16, v137
	v_fmac_f32_e32 v76, 0x3fb504f3, v74
	v_and_b32_e32 v74, 0xffff0000, v137
	v_fmac_f32_e32 v77, 0x3fb504f3, v74
	s_waitcnt vmcnt(14)
	v_lshlrev_b32_e32 v74, 16, v130
	v_fmac_f32_e32 v70, 0x3fb504f3, v74
	v_and_b32_e32 v74, 0xffff0000, v130
	v_fmac_f32_e32 v71, 0x3fb504f3, v74
	v_cvt_pk_bf16_f32 v81, v76, v77
	global_store_dwordx4 v[156:157], v[78:81], off
	v_cvt_pk_bf16_f32 v70, v70, v71
	v_lshlrev_b32_e32 v71, 16, v131
	v_fmac_f32_e32 v72, 0x3fb504f3, v71
	v_and_b32_e32 v71, 0xffff0000, v131
	v_fmac_f32_e32 v73, 0x3fb504f3, v71
	v_cvt_pk_bf16_f32 v71, v72, v73
	v_lshlrev_b32_e32 v72, 16, v132
	v_fmac_f32_e32 v66, 0x3fb504f3, v72
	v_and_b32_e32 v72, 0xffff0000, v132
	v_fmac_f32_e32 v67, 0x3fb504f3, v72
	v_cvt_pk_bf16_f32 v72, v66, v67
	v_lshlrev_b32_e32 v66, 16, v133
	v_fmac_f32_e32 v68, 0x3fb504f3, v66
	v_and_b32_e32 v66, 0xffff0000, v133
	v_lshl_add_u64 v[100:101], v[154:155], 0, s[24:25]
	v_fmac_f32_e32 v69, 0x3fb504f3, v66
	v_cvt_pk_bf16_f32 v73, v68, v69
	global_store_dwordx4 v[156:157], v[70:73], off offset:256
	v_add_co_u32_e32 v102, vcc, s87, v100
	s_waitcnt vmcnt(15)
	v_lshlrev_b32_e32 v106, 16, v196
	v_addc_co_u32_e32 v103, vcc, 0, v101, vcc
	v_add_co_u32_e32 v104, vcc, s91, v100
	v_and_b32_e32 v72, 0xffff0000, v196
	s_nop 0
	v_addc_co_u32_e32 v105, vcc, 0, v101, vcc
	v_add_co_u32_e32 v70, vcc, s86, v100
	v_fmac_f32_e32 v62, 0x3fb504f3, v106
	s_nop 0
	v_addc_co_u32_e32 v71, vcc, 0, v101, vcc
	v_fmac_f32_e32 v63, 0x3fb504f3, v72
	v_cvt_pk_bf16_f32 v62, v62, v63
	v_lshlrev_b32_e32 v63, 16, v197
	v_fmac_f32_e32 v64, 0x3fb504f3, v63
	v_and_b32_e32 v63, 0xffff0000, v197
	v_fmac_f32_e32 v65, 0x3fb504f3, v63
	v_cvt_pk_bf16_f32 v63, v64, v65
	v_lshlrev_b32_e32 v64, 16, v198
	v_fmac_f32_e32 v58, 0x3fb504f3, v64
	v_and_b32_e32 v64, 0xffff0000, v198
	v_fmac_f32_e32 v59, 0x3fb504f3, v64
	v_cvt_pk_bf16_f32 v64, v58, v59
	v_lshlrev_b32_e32 v58, 16, v199
	v_fmac_f32_e32 v60, 0x3fb504f3, v58
	v_and_b32_e32 v58, 0xffff0000, v199
	v_fmac_f32_e32 v61, 0x3fb504f3, v58
	s_waitcnt vmcnt(14)
	v_lshlrev_b32_e32 v58, 16, v200
	v_fmac_f32_e32 v54, 0x3fb504f3, v58
	v_and_b32_e32 v58, 0xffff0000, v200
	v_fmac_f32_e32 v55, 0x3fb504f3, v58
	v_cvt_pk_bf16_f32 v65, v60, v61
	global_store_dwordx4 v[100:101], v[62:65], off
	v_cvt_pk_bf16_f32 v54, v54, v55
	v_lshlrev_b32_e32 v55, 16, v201
	v_fmac_f32_e32 v56, 0x3fb504f3, v55
	v_and_b32_e32 v55, 0xffff0000, v201
	v_fmac_f32_e32 v57, 0x3fb504f3, v55
	v_cvt_pk_bf16_f32 v55, v56, v57
	v_lshlrev_b32_e32 v56, 16, v202
	v_fmac_f32_e32 v50, 0x3fb504f3, v56
	v_and_b32_e32 v56, 0xffff0000, v202
	v_fmac_f32_e32 v51, 0x3fb504f3, v56
	v_cvt_pk_bf16_f32 v56, v50, v51
	v_lshlrev_b32_e32 v50, 16, v203
	v_fmac_f32_e32 v52, 0x3fb504f3, v50
	v_and_b32_e32 v50, 0xffff0000, v203
	v_fmac_f32_e32 v53, 0x3fb504f3, v50
	v_cvt_pk_bf16_f32 v57, v52, v53
	global_store_dwordx4 v[100:101], v[54:57], off offset:256
	s_waitcnt vmcnt(15)
; __device__ __forceinline__ float bflo_(unsigned w) { return __uint_as_float(w << 16); }
; __device__ __forceinline__ float bfhi_(unsigned w) { return __uint_as_float(w & 0xffff0000u); }
; __device__ __forceinline__ unsigned cvt_pk_bf16(float lo, float hi) { unsigned r; asm volatile("v_cvt_pk_bf16_f32 %0, %1, %2" : "=v"(r) : "v"(lo), "v"(hi)); return r; }
; #define PG8_OPQ(p) asm volatile("" : "+v"(p))
;     __device__ __forceinline__ void operator()(const f32x4 (&acc)[2][2][4][2], const Unit& u, int wr, int wc, int fr, int fq) const {
;     ...
;         for (int ai = 0; ai < 2; ++ai) {
;             PG8_OPQ(p);
;             u32x4 h[4][2];
; #pragma unroll
;             for (int m = 0; m < 4; ++m)
; #pragma unroll
;                 for (int bj = 0; bj < 2; ++bj) h[m][bj] = *(const u32x4*)(p + m * step + bj * HALF * 2);
; #pragma unroll
;             for (int m = 0; m < 4; ++m)
; #pragma unroll
;                 for (int bj = 0; bj < 2; ++bj) { const f32x4 v0 = acc[ai][bj][m][0], v1 = acc[ai][bj][m][1]; const u32x4 hh = h[m][bj];
;                     u32x4 w;
;                     w.x = cvt_pk_bf16(bflo_(hh.x) * alpha + v0[0], bfhi_(hh.x) * alpha + v0[1]); w.y = cvt_pk_bf16(bflo_(hh.y) * alpha + v0[2], bfhi_(hh.y) * alpha + v0[3]);
;                     w.z = cvt_pk_bf16(bflo_(hh.z) * alpha + v1[0], bfhi_(hh.z) * alpha + v1[1]); w.w = cvt_pk_bf16(bflo_(hh.w) * alpha + v1[2], bfhi_(hh.w) * alpha + v1[3]);
;                     *(u32x4*)(p + m * step + bj * HALF * 2) = w; }
;             p += 8 * step;
	v_lshlrev_b32_e32 v50, 16, v204
	v_fmac_f32_e32 v46, 0x3fb504f3, v50
	v_and_b32_e32 v50, 0xffff0000, v204
	v_fmac_f32_e32 v47, 0x3fb504f3, v50
	v_cvt_pk_bf16_f32 v46, v46, v47
	v_lshlrev_b32_e32 v47, 16, v205
	v_fmac_f32_e32 v48, 0x3fb504f3, v47
	v_and_b32_e32 v47, 0xffff0000, v205
	v_fmac_f32_e32 v49, 0x3fb504f3, v47
	v_cvt_pk_bf16_f32 v47, v48, v49
	v_lshlrev_b32_e32 v48, 16, v206
	v_fmac_f32_e32 v42, 0x3fb504f3, v48
	v_and_b32_e32 v48, 0xffff0000, v206
	v_fmac_f32_e32 v43, 0x3fb504f3, v48
	v_cvt_pk_bf16_f32 v48, v42, v43
	v_lshlrev_b32_e32 v42, 16, v207
	v_fmac_f32_e32 v44, 0x3fb504f3, v42
	v_and_b32_e32 v42, 0xffff0000, v207
	v_fmac_f32_e32 v45, 0x3fb504f3, v42
	s_waitcnt vmcnt(14)
	v_lshlrev_b32_e32 v42, 16, v208
	v_fmac_f32_e32 v38, 0x3fb504f3, v42
	v_and_b32_e32 v42, 0xffff0000, v208
	v_fmac_f32_e32 v39, 0x3fb504f3, v42
	v_cvt_pk_bf16_f32 v49, v44, v45
	global_store_dwordx4 v[102:103], v[46:49], off
	v_cvt_pk_bf16_f32 v38, v38, v39
	v_lshlrev_b32_e32 v39, 16, v209
	v_fmac_f32_e32 v40, 0x3fb504f3, v39
	v_and_b32_e32 v39, 0xffff0000, v209
	v_fmac_f32_e32 v41, 0x3fb504f3, v39
	v_cvt_pk_bf16_f32 v39, v40, v41
	v_lshlrev_b32_e32 v40, 16, v210
	v_fmac_f32_e32 v34, 0x3fb504f3, v40
	v_and_b32_e32 v40, 0xffff0000, v210
	v_fmac_f32_e32 v35, 0x3fb504f3, v40
	v_cvt_pk_bf16_f32 v40, v34, v35
	v_lshlrev_b32_e32 v34, 16, v211
	v_fmac_f32_e32 v36, 0x3fb504f3, v34
	v_and_b32_e32 v34, 0xffff0000, v211
	v_fmac_f32_e32 v37, 0x3fb504f3, v34
	s_waitcnt vmcnt(14)
	v_lshlrev_b32_e32 v34, 16, v212
	v_fmac_f32_e32 v30, 0x3fb504f3, v34
	v_and_b32_e32 v34, 0xffff0000, v212
	v_fmac_f32_e32 v31, 0x3fb504f3, v34
	v_cvt_pk_bf16_f32 v41, v36, v37
	global_store_dwordx4 v[102:103], v[38:41], off offset:256
	v_cvt_pk_bf16_f32 v30, v30, v31
	v_lshlrev_b32_e32 v31, 16, v213
	v_fmac_f32_e32 v32, 0x3fb504f3, v31
	v_and_b32_e32 v31, 0xffff0000, v213
	v_fmac_f32_e32 v33, 0x3fb504f3, v31
	v_cvt_pk_bf16_f32 v31, v32, v33
	v_lshlrev_b32_e32 v32, 16, v214
	v_fmac_f32_e32 v26, 0x3fb504f3, v32
	v_and_b32_e32 v32, 0xffff0000, v214
	v_fmac_f32_e32 v27, 0x3fb504f3, v32
	v_cvt_pk_bf16_f32 v32, v26, v27
	v_lshlrev_b32_e32 v26, 16, v215
	v_fmac_f32_e32 v28, 0x3fb504f3, v26
	v_and_b32_e32 v26, 0xffff0000, v215
	v_fmac_f32_e32 v29, 0x3fb504f3, v26
	s_waitcnt vmcnt(14)
	v_lshlrev_b32_e32 v26, 16, v216
	v_fmac_f32_e32 v22, 0x3fb504f3, v26
	v_and_b32_e32 v26, 0xffff0000, v216
	v_fmac_f32_e32 v23, 0x3fb504f3, v26
	v_cvt_pk_bf16_f32 v33, v28, v29
	global_store_dwordx4 v[104:105], v[30:33], off
	v_cvt_pk_bf16_f32 v22, v22, v23
	v_lshlrev_b32_e32 v23, 16, v217
	v_fmac_f32_e32 v24, 0x3fb504f3, v23
	v_and_b32_e32 v23, 0xffff0000, v217
	v_fmac_f32_e32 v25, 0x3fb504f3, v23
	v_cvt_pk_bf16_f32 v23, v24, v25
	v_lshlrev_b32_e32 v24, 16, v218
	v_fmac_f32_e32 v18, 0x3fb504f3, v24
	v_and_b32_e32 v24, 0xffff0000, v218
	v_fmac_f32_e32 v19, 0x3fb504f3, v24
	v_cvt_pk_bf16_f32 v24, v18, v19
	v_lshlrev_b32_e32 v18, 16, v219
	v_fmac_f32_e32 v20, 0x3fb504f3, v18
	v_and_b32_e32 v18, 0xffff0000, v219
	v_fmac_f32_e32 v21, 0x3fb504f3, v18
	s_waitcnt vmcnt(14)
	v_lshlrev_b32_e32 v18, 16, v238
	v_fmac_f32_e32 v14, 0x3fb504f3, v18
	v_and_b32_e32 v18, 0xffff0000, v238
	v_fmac_f32_e32 v15, 0x3fb504f3, v18
	v_cvt_pk_bf16_f32 v25, v20, v21
	global_store_dwordx4 v[104:105], v[22:25], off offset:256
	v_cvt_pk_bf16_f32 v14, v14, v15
	v_lshlrev_b32_e32 v15, 16, v239
	v_fmac_f32_e32 v16, 0x3fb504f3, v15
	v_and_b32_e32 v15, 0xffff0000, v239
	v_fmac_f32_e32 v17, 0x3fb504f3, v15
	v_cvt_pk_bf16_f32 v15, v16, v17
	v_lshlrev_b32_e32 v16, 16, v240
	v_fmac_f32_e32 v10, 0x3fb504f3, v16
	v_and_b32_e32 v16, 0xffff0000, v240
	v_fmac_f32_e32 v11, 0x3fb504f3, v16
	v_cvt_pk_bf16_f32 v16, v10, v11
	v_lshlrev_b32_e32 v10, 16, v241
	v_fmac_f32_e32 v12, 0x3fb504f3, v10
	v_and_b32_e32 v10, 0xffff0000, v241
	v_fmac_f32_e32 v13, 0x3fb504f3, v10
	s_waitcnt vmcnt(14)
	v_lshlrev_b32_e32 v10, 16, v244
	v_fmac_f32_e32 v6, 0x3fb504f3, v10
	v_and_b32_e32 v10, 0xffff0000, v244
	v_fmac_f32_e32 v7, 0x3fb504f3, v10
	v_cvt_pk_bf16_f32 v17, v12, v13
	global_store_dwordx4 v[70:71], v[14:17], off
	v_cvt_pk_bf16_f32 v6, v6, v7
	v_lshlrev_b32_e32 v7, 16, v245
	v_fmac_f32_e32 v8, 0x3fb504f3, v7
	v_and_b32_e32 v7, 0xffff0000, v245
	v_fmac_f32_e32 v9, 0x3fb504f3, v7
	v_cvt_pk_bf16_f32 v7, v8, v9
	v_lshlrev_b32_e32 v8, 16, v246
	v_fmac_f32_e32 v2, 0x3fb504f3, v8
	v_and_b32_e32 v8, 0xffff0000, v246
	v_fmac_f32_e32 v3, 0x3fb504f3, v8
	v_cvt_pk_bf16_f32 v8, v2, v3
	v_lshlrev_b32_e32 v2, 16, v247
	v_fmac_f32_e32 v4, 0x3fb504f3, v2
	v_and_b32_e32 v2, 0xffff0000, v247
	v_fmac_f32_e32 v5, 0x3fb504f3, v2
	v_cvt_pk_bf16_f32 v9, v4, v5
	global_store_dwordx4 v[70:71], v[6:9], off offset:256
	s_cbranch_scc1 .LBB0_445
	s_andn2_b64 vcc, exec, s[26:27]
	s_cbranch_vccnz .LBB0_444
	s_barrier
	s_branch .LBB0_444
